# k0 loop layout: X2 falls through into Y (one taken branch less per tile), unneeded s_nop at Y head dropped; one barrier per key tile as v49
# speedup vs baseline: 1.0126x; 1.0080x over previous
; #define LAS __attribute__((address_space(3)))
; template <int DV> ...
;     ...
;             {
;                 bf16x8 kf[8];
; #pragma unroll
;                 for (int d0 = 0; d0 < 4; ++d0) {
;                     kf[2 * d0] = *(const LAS bf16x8*)(Kl + (r32 * KP + 16 * d0 + 8 * hi) * 2);
;                     kf[2 * d0 + 1] = *(const LAS bf16x8*)(Kl + ((32 + r32) * KP + 16 * d0 + 8 * hi) * 2);
;                 }
;                 __builtin_amdgcn_sched_barrier(0);
;                 p0 = __builtin_amdgcn_mfma_f32_32x32x16_bf16(kf[0], qf[0], negm, 0, 0, 0); p1 = __builtin_amdgcn_mfma_f32_32x32x16_bf16(kf[1], qf[0], negm, 0, 0, 0);
; #pragma unroll
;                 for (int d0 = 1; d0 < 4; ++d0) { p0 = __builtin_amdgcn_mfma_f32_32x32x16_bf16(kf[2 * d0], qf[d0], p0, 0, 0, 0); p1 = __builtin_amdgcn_mfma_f32_32x32x16_bf16(kf[2 * d0 + 1], qf[d0], p1, 0, 0, 0); }
;                 __builtin_amdgcn_sched_barrier(0);
;             }
;     ...
;         if (more) {
;             const unsigned bo = ((t + 1) & 1) * ABUFB;
;             *(LAS u32x4*)(lds + bo + kst) = kr;
;             *(LAS u32x4*)(lds + bo + vst) = vr0;
;             if (DV == 128) *(LAS u32x4*)(lds + bo + vst + 64 * VP * 2) = vr1;
;         }
.Lpa_X:
	s_setprio 1
	s_and_b32 s4, s22, 1
	s_mul_i32 s23, s4, 0x6c00
	s_sub_i32 s24, 0x6c00, s23
	v_add_u32_e32 v199, s23, v194
	s_add_i32 s3, s22, 1
	s_mul_hi_u32 s4, s3, 0x55555556
	s_mul_i32 s4, s4, 3
	s_sub_i32 s4, s3, s4
	s_mul_i32 s5, s4, 0x6c00
	v_add_u32_e32 v218, s24, v192
	v_add_u32_e32 v219, s5, v193
.Lpa_Xfirst:
	ds_read_b128 v[142:145], v199
	ds_read_b128 v[146:149], v199 offset:4608
	ds_read_b128 v[150:153], v199 offset:32
	ds_read_b128 v[154:157], v199 offset:4640
	ds_read_b128 v[158:161], v199 offset:64
	ds_read_b128 v[162:165], v199 offset:4672
	ds_read_b128 v[166:169], v199 offset:96
	ds_read_b128 v[170:173], v199 offset:4704
	s_waitcnt lgkmcnt(7)
	v_mfma_f32_32x32x16_bf16 v[98:113], v[142:145], v[126:129], v[66:81]
	s_waitcnt lgkmcnt(5)
	v_mfma_f32_32x32x16_bf16 v[98:113], v[150:153], v[122:125], v[98:113]
	s_waitcnt lgkmcnt(3)
	v_mfma_f32_32x32x16_bf16 v[98:113], v[158:161], v[118:121], v[98:113]
	s_waitcnt lgkmcnt(1)
	v_mfma_f32_32x32x16_bf16 v[98:113], v[166:169], v[114:117], v[98:113]
	v_mfma_f32_32x32x16_bf16 v[82:97], v[146:149], v[126:129], v[66:81]
	v_mfma_f32_32x32x16_bf16 v[82:97], v[154:157], v[122:125], v[82:97]
	v_mfma_f32_32x32x16_bf16 v[82:97], v[162:165], v[118:121], v[82:97]
	s_waitcnt lgkmcnt(0)
	v_mfma_f32_32x32x16_bf16 v[82:97], v[170:173], v[114:117], v[82:97]
	s_waitcnt vmcnt(0)
	s_cmp_lt_i32 s26, 2
	s_cbranch_scc1 .Lpa_nokw
	ds_write_b128 v218, v[130:133]
	ds_write_b128 v219, v[134:137] offset:9216
	ds_write_b128 v219, v[138:141] offset:18432

; #define LAS __attribute__((address_space(3)))
; template <int DV> ...
;     ...
;         if (more) {
;             const unsigned bo = ((t + 1) & 1) * ABUFB;
;             *(LAS u32x4*)(lds + bo + kst) = kr;
;             *(LAS u32x4*)(lds + bo + vst) = vr0;
;             if (DV == 128) *(LAS u32x4*)(lds + bo + vst + 64 * VP * 2) = vr1;
;         }
;         __syncthreads();
.Lpa_noload_first:
	s_waitcnt lgkmcnt(0)
	s_cmp_eq_u32 s25, 0
	s_cbranch_scc1 .Lpa_Y
	s_barrier
	s_branch .Lpa_Y

; __device__ __forceinline__ unsigned cvtpk(float lo, float hi) { const f32x2_t v = {lo, hi}; const bf16x2_t b = __builtin_convertvector(v, bf16x2_t); return __builtin_bit_cast(unsigned, b); }
; template <int DV> ...
;     ...
;             if (first || __any(mx > 8.f)) {
;                 const float dl = first ? mx : fmaxf(mx, 0.f);
;                 const float alpha = first ? 1.f : __builtin_amdgcn_exp2f(-dl);
;                 mref += dl; lrun *= alpha;
; #pragma unroll
;                 for (int r = 0; r < 16; ++r) { p0[r] -= dl; p1[r] -= dl; negm[r] = -mref; }
; #pragma unroll
;                 for (int i = 0; i < DV / 32; ++i)
; #pragma unroll
;                     for (int r = 0; r < 16; ++r) o[i][r] *= alpha;
;                 first = false;
;             }
;             float rs0 = 0.f, rs1 = 0.f;
; #pragma unroll
;             for (int r = 0; r < 16; ++r) { p0[r] = __builtin_amdgcn_exp2f(p0[r]); p1[r] = __builtin_amdgcn_exp2f(p1[r]); rs0 += p0[r]; rs1 += p1[r]; }
;             lrun += rs0 + rs1;
;             bf16x8 pk[4];
;             { u32x4 w;
;               w.x = cvtpk(p0[0], p0[1]); w.y = cvtpk(p0[2], p0[3]); w.z = cvtpk(p0[4], p0[5]); w.w = cvtpk(p0[6], p0[7]); pk[0] = __builtin_bit_cast(bf16x8, w);
;               w.x = cvtpk(p0[8], p0[9]); w.y = cvtpk(p0[10], p0[11]); w.z = cvtpk(p0[12], p0[13]); w.w = cvtpk(p0[14], p0[15]); pk[1] = __builtin_bit_cast(bf16x8, w);
;               w.x = cvtpk(p1[0], p1[1]); w.y = cvtpk(p1[2], p1[3]); w.z = cvtpk(p1[4], p1[5]); w.w = cvtpk(p1[6], p1[7]); pk[2] = __builtin_bit_cast(bf16x8, w);
;               w.x = cvtpk(p1[8], p1[9]); w.y = cvtpk(p1[10], p1[11]); w.z = cvtpk(p1[12], p1[13]); w.w = cvtpk(p1[14], p1[15]); pk[3] = __builtin_bit_cast(bf16x8, w); }
.Lpa_Y:
	s_setprio 0
	s_cmp_eq_u32 s22, 0
	s_cbranch_scc1 .Lpa_slow
	v_exp_f32_e32 v142, v98
	v_exp_f32_e32 v143, v99
	v_exp_f32_e32 v144, v100
	v_exp_f32_e32 v145, v101
	v_exp_f32_e32 v146, v102
	v_exp_f32_e32 v147, v103
	v_exp_f32_e32 v148, v104
	v_exp_f32_e32 v149, v105
	v_exp_f32_e32 v150, v106
	v_exp_f32_e32 v151, v107
	v_exp_f32_e32 v152, v108
	v_exp_f32_e32 v153, v109
	v_exp_f32_e32 v154, v110
	v_exp_f32_e32 v155, v111
	v_exp_f32_e32 v156, v112
	v_exp_f32_e32 v157, v113
	v_exp_f32_e32 v158, v82
	v_exp_f32_e32 v159, v83
	v_exp_f32_e32 v160, v84
	v_exp_f32_e32 v161, v85
	v_exp_f32_e32 v162, v86
	v_exp_f32_e32 v163, v87
	v_exp_f32_e32 v164, v88
	v_exp_f32_e32 v165, v89
	v_exp_f32_e32 v166, v90
	v_exp_f32_e32 v167, v91
	v_exp_f32_e32 v168, v92
	v_exp_f32_e32 v169, v93
	v_exp_f32_e32 v170, v94
	v_exp_f32_e32 v171, v95
	v_exp_f32_e32 v172, v96
	v_exp_f32_e32 v173, v97
	v_add_f32_e32 v198, v142, v143
	v_add_f32_e32 v199, v158, v159
	v_add_f32_e32 v198, v144, v198
	v_add_f32_e32 v199, v160, v199
	v_add_f32_e32 v198, v145, v198
	v_add_f32_e32 v199, v161, v199
	v_add_f32_e32 v198, v146, v198
	v_add_f32_e32 v199, v162, v199
	v_add_f32_e32 v198, v147, v198
	v_add_f32_e32 v199, v163, v199
	v_add_f32_e32 v198, v148, v198
	v_add_f32_e32 v199, v164, v199
	v_add_f32_e32 v198, v149, v198
	v_add_f32_e32 v199, v165, v199
	v_add_f32_e32 v198, v150, v198
	v_add_f32_e32 v199, v166, v199
	v_add_f32_e32 v198, v151, v198
	v_add_f32_e32 v199, v167, v199
	v_add_f32_e32 v198, v152, v198
	v_add_f32_e32 v199, v168, v199
	v_add_f32_e32 v198, v153, v198
	v_add_f32_e32 v199, v169, v199
	v_add_f32_e32 v198, v154, v198
	v_add_f32_e32 v199, v170, v199
	v_add_f32_e32 v198, v155, v198
	v_add_f32_e32 v199, v171, v199
	v_add_f32_e32 v198, v156, v198
	v_add_f32_e32 v199, v172, v199
	v_add_f32_e32 v198, v157, v198
	v_add_f32_e32 v199, v173, v199
	v_add_f32_e32 v198, v199, v198
	v_cmp_lt_f32_e32 vcc, 0x43800000, v198
	v_cvt_pk_bf16_f32 v200, v142, v143
	v_cvt_pk_bf16_f32 v201, v144, v145
	v_cvt_pk_bf16_f32 v202, v146, v147
	v_cvt_pk_bf16_f32 v203, v148, v149
	v_cvt_pk_bf16_f32 v204, v150, v151
	v_cvt_pk_bf16_f32 v205, v152, v153
	v_cvt_pk_bf16_f32 v206, v154, v155
	v_cvt_pk_bf16_f32 v207, v156, v157
	v_cvt_pk_bf16_f32 v210, v158, v159
	v_cvt_pk_bf16_f32 v211, v160, v161
	v_cvt_pk_bf16_f32 v212, v162, v163
	v_cvt_pk_bf16_f32 v213, v164, v165
	v_cvt_pk_bf16_f32 v214, v166, v167
	v_cvt_pk_bf16_f32 v215, v168, v169
	v_cvt_pk_bf16_f32 v216, v170, v171
	v_cvt_pk_bf16_f32 v217, v172, v173
	s_cbranch_vccnz .Lpa_slow
